# residual GEMM phases walk their tile list in reverse (last-written rows first) for better Infinity-Cache reuse between consecutive GEMM phases
# speedup vs baseline: 1.0053x; 1.0053x over previous
;     __host__ __device__ bool next(int i, Unit& u) const {
;         const long L = (long)i * G + c; if (L >= nwg) return false;
;         int wgid = (int)L; { const int q = nwg / NXCD, r = nwg % NXCD, xcd = wgid % NXCD, off = wgid / NXCD; wgid = (xcd < r ? xcd * (q + 1) : r * (q + 1) + (xcd - r) * q) + off; }
;         const int nig = WGM * nN, gid = wgid / nig, fm = gid * WGM, gsz = (nM - fm) < WGM ? (nM - fm) : WGM;
;         u.pm = fm + ((wgid % nig) % gsz); u.pn = (wgid % nig) / gsz; return true;
.LBB0_1173:
	s_ashr_i32 s3, s3, 3
	s_sub_i32 s3, 0x7f, s3
	s_add_i32 s3, s18, s3
	s_ashr_i32 s8, s3, 31
	s_lshr_b32 s8, s8, 27
	s_add_i32 s8, s3, s8
	s_ashr_i32 s9, s8, 5
	s_and_b32 s8, s8, 0xffe0
	s_sub_i32 s3, s3, s8
	s_bfe_i32 s8, s3, 0x80000
	s_bfe_u32 s8, s8, 0x3000c
	s_add_i32 s8, s3, s8
	s_bfe_i32 s11, s8, 0x80000
	s_and_b32 s8, s8, 0xf8
	s_sub_i32 s3, s3, s8
	s_lshl_b32 s9, s9, 3
	s_sext_i32_i16 s11, s11
	s_sext_i32_i8 s3, s3
	s_add_i32 s75, s9, s3
	s_ashr_i32 s40, s11, 3

;     __host__ __device__ bool next(int i, Unit& u) const {
;         const long L = (long)i * G + c; if (L >= nwg) return false;
;         int wgid = (int)L; { const int q = nwg / NXCD, r = nwg % NXCD, xcd = wgid % NXCD, off = wgid / NXCD; wgid = (xcd < r ? xcd * (q + 1) : r * (q + 1) + (xcd - r) * q) + off; }
;         const int nig = WGM * nN, gid = wgid / nig, fm = gid * WGM, gsz = (nM - fm) < WGM ? (nM - fm) : WGM;
;         u.pm = fm + ((wgid % nig) % gsz); u.pn = (wgid % nig) / gsz; return true;
.LBB0_1185:
	s_ashr_i32 s6, s48, 3
	s_sub_i32 s6, 0x7f, s6
	s_add_i32 s6, s74, s6
	s_ashr_i32 s7, s6, 31
	s_lshr_b32 s7, s7, 27
	s_add_i32 s7, s6, s7
	s_ashr_i32 s48, s7, 5
	s_lshl_b32 s48, s48, 3
	s_sub_i32 s49, 0x100, s48
	s_min_i32 s49, s49, 8
	s_abs_i32 s74, s49
	v_cvt_f32_u32_e32 v0, s74
	s_sub_i32 s77, 0, s74
	s_andn2_b32 s7, s7, 31
	s_sub_i32 s6, s6, s7
	v_rcp_iflag_f32_e32 v0, v0
	s_abs_i32 s7, s6
	s_xor_b32 s76, s6, s49
	s_ashr_i32 s76, s76, 31
	v_mul_f32_e32 v0, 0x4f7ffffe, v0
	v_cvt_u32_f32_e32 v0, v0
	s_nop 0
	v_readfirstlane_b32 s80, v0
	s_mul_i32 s77, s77, s80
	s_mul_hi_u32 s77, s80, s77
	s_add_i32 s80, s80, s77
	s_mul_hi_u32 s77, s7, s80
	s_mul_i32 s80, s77, s74
	s_sub_i32 s7, s7, s80
	s_add_i32 s81, s77, 1
	s_sub_i32 s80, s7, s74
	s_cmp_ge_u32 s7, s74
	s_cselect_b32 s77, s81, s77
	s_cselect_b32 s7, s80, s7
	s_add_i32 s80, s77, 1
	s_cmp_ge_u32 s7, s74
	s_cselect_b32 s7, s80, s77
	s_xor_b32 s7, s7, s76
	s_sub_i32 s74, s7, s76
	s_mul_i32 s7, s74, s49
	s_sub_i32 s6, s6, s7
	s_add_i32 s76, s48, s6
